# code placement: the five K-loop heads aligned to 256 bytes
# speedup vs baseline: 1.0119x; 1.0119x over previous
.LBB0_169:
	s_ashr_i32 s51, s50, 31
	s_lshl_b64 s[12:13], s[50:51], 19
	s_add_u32 s52, s17, s12
	s_addc_u32 s53, s60, s13
	s_and_b64 s[12:13], s[40:41], exec
	s_cselect_b32 s3, s53, s9
	s_cselect_b32 s24, s52, s8
	s_ashr_i32 s49, s48, 31
	s_lshl_b64 s[12:13], s[48:49], 19
	s_add_u32 s54, s82, s12
	s_addc_u32 s55, s83, s13
	s_and_b64 s[12:13], s[40:41], exec
	s_cselect_b32 s25, s55, s11
	s_cselect_b32 s26, s54, s10
	s_add_u32 s8, s8, 0x40080
	s_addc_u32 s9, s9, 0
	s_add_u32 s27, s10, 0x100
	v_mov_b32_e32 v2, 0
	s_addc_u32 s28, s11, 0
	s_mov_b32 s29, -2
	v_mov_b64_e32 v[2:3], 0
	v_mov_b64_e32 v[4:5], 0
	v_mov_b64_e32 v[6:7], 0
	v_mov_b64_e32 v[8:9], 0
	v_mov_b64_e32 v[10:11], 0
	v_mov_b64_e32 v[12:13], 0
	v_mov_b64_e32 v[14:15], 0
	v_mov_b64_e32 v[16:17], 0
	v_mov_b64_e32 v[18:19], 0
	v_mov_b64_e32 v[20:21], 0
	v_mov_b64_e32 v[22:23], 0
	v_mov_b64_e32 v[24:25], 0
	v_mov_b64_e32 v[26:27], 0
	v_mov_b64_e32 v[28:29], 0
	v_mov_b64_e32 v[30:31], 0
	v_mov_b64_e32 v[32:33], 0
	v_mov_b64_e32 v[34:35], 0
	v_mov_b64_e32 v[36:37], 0
	v_mov_b64_e32 v[38:39], 0
	v_mov_b64_e32 v[40:41], 0
	v_mov_b64_e32 v[42:43], 0
	v_mov_b64_e32 v[44:45], 0
	v_mov_b64_e32 v[46:47], 0
	v_mov_b64_e32 v[48:49], 0
	v_mov_b64_e32 v[50:51], 0
	v_mov_b64_e32 v[52:53], 0
	v_mov_b64_e32 v[54:55], 0
	v_mov_b64_e32 v[56:57], 0
	v_mov_b64_e32 v[58:59], 0
	v_mov_b64_e32 v[60:61], 0
	v_mov_b64_e32 v[62:63], 0
	v_mov_b64_e32 v[64:65], 0
	v_mov_b64_e32 v[66:67], 0
	v_mov_b64_e32 v[68:69], 0
	v_mov_b64_e32 v[70:71], 0
	v_mov_b64_e32 v[72:73], 0
	v_mov_b64_e32 v[74:75], 0
	v_mov_b64_e32 v[76:77], 0
	v_mov_b64_e32 v[78:79], 0
	v_mov_b64_e32 v[80:81], 0
	v_mov_b64_e32 v[82:83], 0
	v_mov_b64_e32 v[84:85], 0
	v_mov_b64_e32 v[86:87], 0
	v_mov_b64_e32 v[88:89], 0
	v_mov_b64_e32 v[90:91], 0
	v_mov_b64_e32 v[92:93], 0
	v_mov_b64_e32 v[94:95], 0
	v_mov_b64_e32 v[96:97], 0
	v_mov_b64_e32 v[98:99], 0
	v_mov_b64_e32 v[100:101], 0
	v_mov_b64_e32 v[102:103], 0
	v_mov_b64_e32 v[104:105], 0
	v_mov_b64_e32 v[106:107], 0
	v_mov_b64_e32 v[108:109], 0
	v_mov_b64_e32 v[110:111], 0
	v_mov_b64_e32 v[112:113], 0
	v_mov_b64_e32 v[114:115], 0
	v_mov_b64_e32 v[116:117], 0
	v_mov_b64_e32 v[118:119], 0
	v_mov_b64_e32 v[120:121], 0
	v_mov_b64_e32 v[122:123], 0
	v_mov_b64_e32 v[124:125], 0
	v_mov_b64_e32 v[126:127], 0
	v_mov_b64_e32 v[128:129], 0
	.p2align	8

.Lp5_noearly:
	s_barrier
	s_add_i32 s68, s68, 2
	s_add_u32 s10, s10, 0x100
	s_addc_u32 s11, s11, 0
	s_cmp_gt_u32 s68, 13
	s_cbranch_scc1 .LBB0_549
	.p2align	8

.LBB0_639:
	s_ashr_i32 s49, s48, 31
	s_lshl_b64 s[14:15], s[48:49], 19
	v_readlane_b32 s11, v254, 16
	s_add_u32 s50, s11, s14
	v_readlane_b32 s11, v254, 17
	s_addc_u32 s51, s11, s15
	s_and_b64 s[14:15], s[42:43], exec
	s_cselect_b32 s11, s51, s13
	s_cselect_b32 s14, s50, s12
	s_ashr_i32 s47, s46, 31
	s_lshl_b64 s[24:25], s[46:47], 19
	s_add_u32 s52, s74, s24
	s_addc_u32 s53, s75, s25
	s_and_b64 s[24:25], s[42:43], exec
	s_cselect_b32 s15, s53, s55
	s_cselect_b32 s24, s52, s54
	s_add_u32 s12, s12, 0x40080
	s_addc_u32 s13, s13, 0
	s_add_u32 s25, s54, 0x100
	v_mov_b32_e32 v0, 0
	s_addc_u32 s26, s55, 0
	s_mov_b32 s27, -2
	s_waitcnt lgkmcnt(0)
	v_mov_b64_e32 v[0:1], 0
	v_mov_b64_e32 v[2:3], 0
	v_mov_b64_e32 v[4:5], 0
	v_mov_b64_e32 v[6:7], 0
	v_mov_b64_e32 v[8:9], 0
	v_mov_b64_e32 v[10:11], 0
	v_mov_b64_e32 v[12:13], 0
	v_mov_b64_e32 v[14:15], 0
	v_mov_b64_e32 v[16:17], 0
	v_mov_b64_e32 v[18:19], 0
	v_mov_b64_e32 v[20:21], 0
	v_mov_b64_e32 v[22:23], 0
	v_mov_b64_e32 v[24:25], 0
	v_mov_b64_e32 v[26:27], 0
	v_mov_b64_e32 v[28:29], 0
	v_mov_b64_e32 v[30:31], 0
	v_mov_b64_e32 v[32:33], 0
	v_mov_b64_e32 v[34:35], 0
	v_mov_b64_e32 v[36:37], 0
	v_mov_b64_e32 v[38:39], 0
	v_mov_b64_e32 v[40:41], 0
	v_mov_b64_e32 v[42:43], 0
	v_mov_b64_e32 v[44:45], 0
	v_mov_b64_e32 v[46:47], 0
	v_mov_b64_e32 v[48:49], 0
	v_mov_b64_e32 v[50:51], 0
	v_mov_b64_e32 v[52:53], 0
	v_mov_b64_e32 v[54:55], 0
	v_mov_b64_e32 v[56:57], 0
	v_mov_b64_e32 v[58:59], 0
	v_mov_b64_e32 v[60:61], 0
	v_mov_b64_e32 v[62:63], 0
	v_mov_b64_e32 v[64:65], 0
	v_mov_b64_e32 v[66:67], 0
	v_mov_b64_e32 v[68:69], 0
	v_mov_b64_e32 v[70:71], 0
	v_mov_b64_e32 v[72:73], 0
	v_mov_b64_e32 v[74:75], 0
	v_mov_b64_e32 v[76:77], 0
	v_mov_b64_e32 v[78:79], 0
	v_mov_b64_e32 v[80:81], 0
	v_mov_b64_e32 v[82:83], 0
	v_mov_b64_e32 v[84:85], 0
	v_mov_b64_e32 v[86:87], 0
	v_mov_b64_e32 v[88:89], 0
	v_mov_b64_e32 v[90:91], 0
	v_mov_b64_e32 v[92:93], 0
	v_mov_b64_e32 v[94:95], 0
	v_mov_b64_e32 v[96:97], 0
	v_mov_b64_e32 v[98:99], 0
	v_mov_b64_e32 v[100:101], 0
	v_mov_b64_e32 v[102:103], 0
	v_mov_b64_e32 v[104:105], 0
	v_mov_b64_e32 v[106:107], 0
	v_mov_b64_e32 v[108:109], 0
	v_mov_b64_e32 v[110:111], 0
	v_mov_b64_e32 v[112:113], 0
	v_mov_b64_e32 v[114:115], 0
	v_mov_b64_e32 v[116:117], 0
	v_mov_b64_e32 v[118:119], 0
	v_mov_b64_e32 v[120:121], 0
	v_mov_b64_e32 v[122:123], 0
	v_mov_b64_e32 v[124:125], 0
	v_mov_b64_e32 v[126:127], 0
	.p2align	8

.LBB0_743:
	s_ashr_i32 s81, s80, 31
	s_lshl_b64 s[14:15], s[80:81], 19
	s_add_u32 s82, s96, s14
	s_addc_u32 s83, s97, s15
	s_and_b64 s[14:15], s[44:45], exec
	s_cselect_b32 s11, s83, s47
	s_cselect_b32 s14, s82, s46
	s_ashr_i32 s75, s74, 31
	s_lshl_b64 s[16:17], s[74:75], 19
	v_readlane_b32 s24, v254, 6
	v_readlane_b32 s25, v254, 7
	s_add_u32 s84, s24, s16
	s_addc_u32 s85, s25, s17
	s_and_b64 s[16:17], s[44:45], exec
	s_cselect_b32 s15, s85, s49
	s_cselect_b32 s16, s84, s48
	s_add_u32 s46, s46, 0x40080
	s_addc_u32 s47, s47, 0
	s_add_u32 s17, s48, 0x100
	v_mov_b32_e32 v64, 0
	s_addc_u32 s24, s49, 0
	s_mov_b32 s25, -2
	v_mov_b64_e32 v[0:1], 0
	v_mov_b64_e32 v[2:3], 0
	v_mov_b64_e32 v[4:5], 0
	v_mov_b64_e32 v[6:7], 0
	v_mov_b64_e32 v[8:9], 0
	v_mov_b64_e32 v[10:11], 0
	v_mov_b64_e32 v[12:13], 0
	v_mov_b64_e32 v[14:15], 0
	v_mov_b64_e32 v[16:17], 0
	v_mov_b64_e32 v[18:19], 0
	v_mov_b64_e32 v[20:21], 0
	v_mov_b64_e32 v[22:23], 0
	v_mov_b64_e32 v[24:25], 0
	v_mov_b64_e32 v[26:27], 0
	v_mov_b64_e32 v[28:29], 0
	v_mov_b64_e32 v[30:31], 0
	v_mov_b64_e32 v[32:33], 0
	v_mov_b64_e32 v[34:35], 0
	v_mov_b64_e32 v[36:37], 0
	v_mov_b64_e32 v[38:39], 0
	v_mov_b64_e32 v[40:41], 0
	v_mov_b64_e32 v[42:43], 0
	v_mov_b64_e32 v[44:45], 0
	v_mov_b64_e32 v[46:47], 0
	v_mov_b64_e32 v[48:49], 0
	v_mov_b64_e32 v[50:51], 0
	v_mov_b64_e32 v[52:53], 0
	v_mov_b64_e32 v[54:55], 0
	v_mov_b64_e32 v[56:57], 0
	v_mov_b64_e32 v[58:59], 0
	v_mov_b64_e32 v[60:61], 0
	v_mov_b64_e32 v[62:63], 0
	v_mov_b64_e32 v[64:65], 0
	v_mov_b64_e32 v[66:67], 0
	v_mov_b64_e32 v[68:69], 0
	v_mov_b64_e32 v[70:71], 0
	v_mov_b64_e32 v[72:73], 0
	v_mov_b64_e32 v[74:75], 0
	v_mov_b64_e32 v[76:77], 0
	v_mov_b64_e32 v[78:79], 0
	v_mov_b64_e32 v[96:97], 0
	v_mov_b64_e32 v[98:99], 0
	v_mov_b64_e32 v[100:101], 0
	v_mov_b64_e32 v[102:103], 0
	v_mov_b64_e32 v[104:105], 0
	v_mov_b64_e32 v[106:107], 0
	v_mov_b64_e32 v[108:109], 0
	v_mov_b64_e32 v[110:111], 0
	v_mov_b64_e32 v[112:113], 0
	v_mov_b64_e32 v[114:115], 0
	v_mov_b64_e32 v[116:117], 0
	v_mov_b64_e32 v[118:119], 0
	v_mov_b64_e32 v[120:121], 0
	v_mov_b64_e32 v[122:123], 0
	v_mov_b64_e32 v[124:125], 0
	v_mov_b64_e32 v[126:127], 0
	v_mov_b64_e32 v[136:137], 0
	v_mov_b64_e32 v[138:139], 0
	v_mov_b64_e32 v[140:141], 0
	v_mov_b64_e32 v[142:143], 0
	v_mov_b64_e32 v[144:145], 0
	v_mov_b64_e32 v[146:147], 0
	v_mov_b64_e32 v[148:149], 0
	v_mov_b64_e32 v[150:151], 0
	.p2align	8

.LBB0_954:
	s_add_u32 s13, s46, 0x100
	v_mov_b32_e32 v0, 0
	s_addc_u32 s14, s47, 0
	s_mov_b32 s15, -2
	v_mov_b64_e32 v[0:1], 0
	v_mov_b64_e32 v[2:3], 0
	v_mov_b64_e32 v[4:5], 0
	v_mov_b64_e32 v[6:7], 0
	v_mov_b64_e32 v[8:9], 0
	v_mov_b64_e32 v[10:11], 0
	v_mov_b64_e32 v[12:13], 0
	v_mov_b64_e32 v[14:15], 0
	v_mov_b64_e32 v[16:17], 0
	v_mov_b64_e32 v[18:19], 0
	v_mov_b64_e32 v[20:21], 0
	v_mov_b64_e32 v[22:23], 0
	v_mov_b64_e32 v[24:25], 0
	v_mov_b64_e32 v[26:27], 0
	v_mov_b64_e32 v[28:29], 0
	v_mov_b64_e32 v[30:31], 0
	v_mov_b64_e32 v[32:33], 0
	v_mov_b64_e32 v[34:35], 0
	v_mov_b64_e32 v[36:37], 0
	v_mov_b64_e32 v[38:39], 0
	v_mov_b64_e32 v[40:41], 0
	v_mov_b64_e32 v[42:43], 0
	v_mov_b64_e32 v[44:45], 0
	v_mov_b64_e32 v[46:47], 0
	v_mov_b64_e32 v[48:49], 0
	v_mov_b64_e32 v[50:51], 0
	v_mov_b64_e32 v[52:53], 0
	v_mov_b64_e32 v[54:55], 0
	v_mov_b64_e32 v[56:57], 0
	v_mov_b64_e32 v[58:59], 0
	v_mov_b64_e32 v[60:61], 0
	v_mov_b64_e32 v[62:63], 0
	v_mov_b64_e32 v[64:65], 0
	v_mov_b64_e32 v[66:67], 0
	v_mov_b64_e32 v[68:69], 0
	v_mov_b64_e32 v[70:71], 0
	v_mov_b64_e32 v[72:73], 0
	v_mov_b64_e32 v[74:75], 0
	v_mov_b64_e32 v[76:77], 0
	v_mov_b64_e32 v[78:79], 0
	v_mov_b64_e32 v[80:81], 0
	v_mov_b64_e32 v[82:83], 0
	v_mov_b64_e32 v[84:85], 0
	v_mov_b64_e32 v[86:87], 0
	v_mov_b64_e32 v[88:89], 0
	v_mov_b64_e32 v[90:91], 0
	v_mov_b64_e32 v[92:93], 0
	v_mov_b64_e32 v[94:95], 0
	v_mov_b64_e32 v[96:97], 0
	v_mov_b64_e32 v[98:99], 0
	v_mov_b64_e32 v[100:101], 0
	v_mov_b64_e32 v[102:103], 0
	v_mov_b64_e32 v[104:105], 0
	v_mov_b64_e32 v[106:107], 0
	v_mov_b64_e32 v[108:109], 0
	v_mov_b64_e32 v[110:111], 0
	v_mov_b64_e32 v[112:113], 0
	v_mov_b64_e32 v[114:115], 0
	v_mov_b64_e32 v[116:117], 0
	v_mov_b64_e32 v[118:119], 0
	v_mov_b64_e32 v[120:121], 0
	v_mov_b64_e32 v[122:123], 0
	v_mov_b64_e32 v[124:125], 0
	v_mov_b64_e32 v[126:127], 0
	.p2align	8
